# FFN-up idle-workgroup conversion: tile loads issued in four groups with a short sleep between groups (smoother HBM request stream beside the GEMM round)
# speedup vs baseline: 1.0129x; 1.0129x over previous
; __device__ __forceinline__ void tr_load(const TrJob& jb, int tile, int tid, f32x4 (&v)[8][2], int& k0, int& n0) {
;     const int nblk = (jb.N + 127) / 128, kt = tile / nblk, nt = tile - kt * nblk; k0 = 256 * kt; n0 = 128 * nt;
;     const int c4 = (tid & 15) + 16 * ((tid >> 6) & 1), rp = ((tid >> 4) & 3) + 4 * (tid >> 7);
;     int col = n0 + 4 * c4; col = col < jb.N - 4 ? col : jb.N - 4;
;     const float* wp = jb.W + (size_t)(k0 + 2 * rp) * jb.N + col;
; #pragma unroll
;     for (int i = 0; i < 8; ++i) { v[i][0] = *(const f32x4*)(wp + (size_t)(32 * i) * jb.N); v[i][1] = *(const f32x4*)(wp + (size_t)(32 * i + 1) * jb.N); }
;     if (jb.gain) {
; #pragma unroll
;         for (int i = 0; i < 8; ++i) { const float ga = jb.gain[k0 + 32 * i + 2 * rp], gb = jb.gain[k0 + 32 * i + 2 * rp + 1]; v[i][0] = v[i][0] * ga; v[i][1] = v[i][1] * gb; } }
.LBB0_385:
	s_add_i32 s10, s34, 0x7f
	s_lshr_b32 s10, s10, 7
	v_cvt_f32_u32_e32 v2, s10
	s_sub_i32 s15, 0, s10
	s_abs_i32 s14, s40
	s_ashr_i32 s11, s40, 31
	v_rcp_iflag_f32_e32 v2, v2
	s_nop 0
	v_mul_f32_e32 v2, 0x4f7ffffe, v2
	v_cvt_u32_f32_e32 v2, v2
	s_nop 0
	v_readfirstlane_b32 s16, v2
	s_mul_i32 s15, s15, s16
	s_mul_hi_u32 s15, s16, s15
	s_add_i32 s16, s16, s15
	s_mul_hi_u32 s15, s14, s16
	s_mul_i32 s16, s15, s10
	s_sub_i32 s14, s14, s16
	s_add_i32 s17, s15, 1
	s_sub_i32 s16, s14, s10
	s_cmp_ge_u32 s14, s10
	s_cselect_b32 s15, s17, s15
	s_cselect_b32 s14, s16, s14
	s_add_i32 s16, s15, 1
	s_cmp_ge_u32 s14, s10
	s_cselect_b32 s14, s16, s15
	s_xor_b32 s14, s14, s11
	s_sub_i32 s11, s14, s11
	s_mul_i32 s10, s11, s10
	s_lshl_b32 s14, s11, 8
	s_sub_i32 s10, s40, s10
	v_add_u32_e32 v68, s14, v78
	s_lshl_b32 s15, s10, 7
	s_add_i32 s16, s34, -4
	v_or_b32_e32 v2, s15, v77
	v_mad_u64_u32 v[6:7], s[10:11], v68, s34, 0
	v_ashrrev_i32_e32 v69, 31, v68
	v_min_i32_e32 v4, s16, v2
	v_mov_b32_e32 v2, v7
	v_mad_u64_u32 v[8:9], s[10:11], v69, s34, v[2:3]
	v_mov_b32_e32 v7, v8
	v_lshl_add_u64 v[6:7], v[6:7], 2, s[12:13]
	v_ashrrev_i32_e32 v5, 31, v4
	v_lshl_add_u64 v[4:5], v[4:5], 2, v[6:7]
	s_lshl_b64 s[10:11], s[34:35], 2
	v_lshl_add_u64 v[12:13], v[4:5], 0, s[10:11]
	s_mul_i32 s12, s34, 0x7c
	s_mov_b32 s13, s35
	global_load_dwordx4 v[4:7], v[4:5], off sc1 nt
	s_nop 0
	global_load_dwordx4 v[8:11], v[12:13], off sc1 nt
	v_lshl_add_u64 v[12:13], v[12:13], 0, s[12:13]
	v_lshl_add_u64 v[20:21], v[12:13], 0, s[10:11]
	global_load_dwordx4 v[12:15], v[12:13], off sc1 nt
	s_nop 0
	global_load_dwordx4 v[16:19], v[20:21], off sc1 nt
	s_sleep 3
	v_lshl_add_u64 v[20:21], v[20:21], 0, s[12:13]
	v_lshl_add_u64 v[28:29], v[20:21], 0, s[10:11]
	global_load_dwordx4 v[20:23], v[20:21], off sc1 nt
	s_nop 0
	global_load_dwordx4 v[24:27], v[28:29], off sc1 nt
	v_lshl_add_u64 v[28:29], v[28:29], 0, s[12:13]
	v_lshl_add_u64 v[36:37], v[28:29], 0, s[10:11]
	v_lshl_add_u64 v[40:41], v[36:37], 0, s[12:13]
	v_lshl_add_u64 v[44:45], v[40:41], 0, s[10:11]
	v_lshl_add_u64 v[48:49], v[44:45], 0, s[12:13]
	v_lshl_add_u64 v[52:53], v[48:49], 0, s[10:11]
	v_lshl_add_u64 v[56:57], v[52:53], 0, s[12:13]
	v_lshl_add_u64 v[60:61], v[56:57], 0, s[10:11]
	v_lshl_add_u64 v[64:65], v[60:61], 0, s[12:13]
	global_load_dwordx4 v[28:31], v[28:29], off sc1 nt
	s_nop 0
	global_load_dwordx4 v[32:35], v[36:37], off sc1 nt
	s_sleep 3
	s_cmp_eq_u64 s[8:9], 0
	global_load_dwordx4 v[36:39], v[40:41], off sc1 nt
	s_nop 0
	global_load_dwordx4 v[40:43], v[44:45], off sc1 nt
	s_nop 0
	global_load_dwordx4 v[44:47], v[48:49], off sc1 nt
	s_nop 0
	global_load_dwordx4 v[48:51], v[52:53], off sc1 nt
	s_sleep 3
	s_nop 0
	global_load_dwordx4 v[52:55], v[56:57], off sc1 nt
	s_nop 0
	global_load_dwordx4 v[56:59], v[60:61], off sc1 nt
	s_nop 0
	global_load_dwordx4 v[60:63], v[64:65], off sc1 nt
	v_lshl_add_u64 v[64:65], v[64:65], 0, s[10:11]
	global_load_dwordx4 v[64:67], v[64:65], off sc1 nt
	s_cbranch_scc1 .LBB0_387
	v_lshl_add_u64 v[70:71], v[68:69], 2, s[8:9]
	global_load_dwordx2 v[70:71], v[70:71], off
	s_waitcnt vmcnt(0)
	v_pk_mul_f32 v[6:7], v[6:7], v[70:71] op_sel_hi:[1,0]
	v_pk_mul_f32 v[4:5], v[4:5], v[70:71] op_sel_hi:[1,0]
	v_pk_mul_f32 v[10:11], v[10:11], v[70:71] op_sel:[0,1]
	v_pk_mul_f32 v[8:9], v[8:9], v[70:71] op_sel:[0,1]
	v_add_u32_e32 v70, 32, v68
	v_ashrrev_i32_e32 v71, 31, v70
	v_lshl_add_u64 v[70:71], v[70:71], 2, s[8:9]
	global_load_dwordx2 v[70:71], v[70:71], off
	s_waitcnt vmcnt(0)
	v_pk_mul_f32 v[14:15], v[14:15], v[70:71] op_sel_hi:[1,0]
	v_pk_mul_f32 v[12:13], v[12:13], v[70:71] op_sel_hi:[1,0]
	v_pk_mul_f32 v[18:19], v[18:19], v[70:71] op_sel:[0,1]
	v_pk_mul_f32 v[16:17], v[16:17], v[70:71] op_sel:[0,1]
	v_add_u32_e32 v70, 64, v68
	v_ashrrev_i32_e32 v71, 31, v70
	v_lshl_add_u64 v[70:71], v[70:71], 2, s[8:9]
	global_load_dwordx2 v[70:71], v[70:71], off
	s_waitcnt vmcnt(0)
	v_pk_mul_f32 v[22:23], v[22:23], v[70:71] op_sel_hi:[1,0]
	v_pk_mul_f32 v[20:21], v[20:21], v[70:71] op_sel_hi:[1,0]
	v_pk_mul_f32 v[26:27], v[26:27], v[70:71] op_sel:[0,1]
	v_pk_mul_f32 v[24:25], v[24:25], v[70:71] op_sel:[0,1]
	v_add_u32_e32 v70, 0x60, v68
	v_ashrrev_i32_e32 v71, 31, v70
	v_lshl_add_u64 v[70:71], v[70:71], 2, s[8:9]
	global_load_dwordx2 v[70:71], v[70:71], off
	s_waitcnt vmcnt(0)
	v_pk_mul_f32 v[30:31], v[30:31], v[70:71] op_sel_hi:[1,0]
	v_pk_mul_f32 v[28:29], v[28:29], v[70:71] op_sel_hi:[1,0]
	v_pk_mul_f32 v[34:35], v[34:35], v[70:71] op_sel:[0,1]
	v_pk_mul_f32 v[32:33], v[32:33], v[70:71] op_sel:[0,1]
	v_add_u32_e32 v70, 0x80, v68
	v_ashrrev_i32_e32 v71, 31, v70
	v_lshl_add_u64 v[70:71], v[70:71], 2, s[8:9]
	global_load_dwordx2 v[70:71], v[70:71], off
	s_waitcnt vmcnt(0)
	v_pk_mul_f32 v[38:39], v[38:39], v[70:71] op_sel_hi:[1,0]
	v_pk_mul_f32 v[36:37], v[36:37], v[70:71] op_sel_hi:[1,0]
	v_pk_mul_f32 v[42:43], v[42:43], v[70:71] op_sel:[0,1]
	v_pk_mul_f32 v[40:41], v[40:41], v[70:71] op_sel:[0,1]
	v_add_u32_e32 v70, 0xa0, v68
	v_ashrrev_i32_e32 v71, 31, v70
	v_lshl_add_u64 v[70:71], v[70:71], 2, s[8:9]
	global_load_dwordx2 v[70:71], v[70:71], off
	s_waitcnt vmcnt(0)
	v_pk_mul_f32 v[46:47], v[46:47], v[70:71] op_sel_hi:[1,0]
	v_pk_mul_f32 v[44:45], v[44:45], v[70:71] op_sel_hi:[1,0]
	v_pk_mul_f32 v[50:51], v[50:51], v[70:71] op_sel:[0,1]
	v_pk_mul_f32 v[48:49], v[48:49], v[70:71] op_sel:[0,1]
	v_add_u32_e32 v70, 0xc0, v68
	v_add_u32_e32 v68, 0xe0, v68
	v_ashrrev_i32_e32 v71, 31, v70
	v_ashrrev_i32_e32 v69, 31, v68
	v_lshl_add_u64 v[70:71], v[70:71], 2, s[8:9]
	v_lshl_add_u64 v[68:69], v[68:69], 2, s[8:9]
	global_load_dwordx2 v[70:71], v[70:71], off
	s_nop 0
	global_load_dwordx2 v[68:69], v[68:69], off
	s_waitcnt vmcnt(1)
	v_pk_mul_f32 v[54:55], v[54:55], v[70:71] op_sel_hi:[1,0]
	v_pk_mul_f32 v[52:53], v[52:53], v[70:71] op_sel_hi:[1,0]
	v_pk_mul_f32 v[58:59], v[58:59], v[70:71] op_sel:[0,1]
	v_pk_mul_f32 v[56:57], v[56:57], v[70:71] op_sel:[0,1]
	s_waitcnt vmcnt(0)
	v_pk_mul_f32 v[62:63], v[62:63], v[68:69] op_sel_hi:[1,0]
	v_pk_mul_f32 v[60:61], v[60:61], v[68:69] op_sel_hi:[1,0]
	v_pk_mul_f32 v[66:67], v[66:67], v[68:69] op_sel:[0,1]
	v_pk_mul_f32 v[64:65], v[64:65], v[68:69] op_sel:[0,1]
